# scan: the ticket fetch no longer waits for the previous unit's final-state stores (vmcnt(0) only at a workgroup's first ticket; afterwards the prefetched ticket is known to have landed at a chunk-top
# speedup vs baseline: 1.0143x; 1.0040x over previous
.Lscan_setup:
	s_add_u32 s0, s28, 0x14500000
	v_writelane_b32 v254, s0, 50
	s_addc_u32 s0, s29, 0
	v_writelane_b32 v254, s0, 51
	s_add_u32 s0, s28, 0x3800
	s_addc_u32 s1, s29, 0
	v_writelane_b32 v254, s0, 52
	s_mov_b32 s32, 0
	s_mov_b64 s[98:99], exec
	s_and_b64 exec, exec, s[56:57]
	s_cbranch_execz .Lq_noprime
	v_mov_b32_e32 v0, 0
	v_mov_b32_e32 v255, 1
	global_atomic_add v255, v0, v255, s[0:1] sc0

.LBB0_580:
	s_mov_b32 s16, 2
	s_and_b64 vcc, exec, s[78:79]
	s_cbranch_vccz .LBB0_589
	s_xor_b64 s[16:17], s[70:71], -1
	s_mov_b64 s[74:75], -1
	s_and_b64 vcc, exec, s[16:17]
	s_mov_b32 s17, s86
	s_mov_b64 s[76:77], s[24:25]
	s_mov_b64 s[46:47], -1
	s_cbranch_vccz .LBB0_590
	s_barrier
	s_and_saveexec_b64 s[46:47], s[4:5]
	s_cbranch_execz .LBB0_586
	s_mov_b64 s[74:75], exec
	v_mbcnt_lo_u32_b32 v0, s74, 0
	v_mbcnt_hi_u32_b32 v0, s75, v0
	v_cmp_eq_u32_e32 vcc, 0, v0
	s_and_saveexec_b64 s[70:71], vcc
	s_cbranch_execz .LBB0_585
	s_cmp_lg_u32 s32, 0
	s_cbranch_scc1 .Ltk_ready
	s_waitcnt vmcnt(0)
.Ltk_ready:
	s_mov_b32 s32, 1
	v_mov_b32_e32 v2, v255
	v_mov_b32_e32 v255, 1
	v_readlane_b32 s16, v254, 52
	v_readlane_b32 s17, v254, 53
	s_nop 4
	global_atomic_add v255, v1, v255, s[16:17] sc0
	s_nop 0
